# RG-LRU pass-1 scan: the 20 LDS reads of each 8-token trip issued together with counted lgkmcnt hand-over (was read+full wait each); MoBA state merge: 4 LDS row reads batched
# speedup vs baseline: 1.0066x; 1.0051x over previous
.LBB0_326:
	ds_read_u16 v216, v20 offset:32768
	ds_read_u16 v217, v20 offset:33280
	ds_read2st64_b32 v[218:219], v3 offset1:4
	ds_read_u16 v220, v20 offset:49152
	ds_read_u16 v221, v20 offset:49664
	ds_read_u16 v222, v20 offset:33792
	ds_read_u16 v223, v20 offset:50176
	ds_read2st64_b32 v[224:225], v3 offset0:8 offset1:12
	ds_read_u16 v226, v20 offset:34304
	ds_read_u16 v227, v20 offset:50688
	ds_read_u16 v228, v20 offset:34816
	ds_read_u16 v229, v20 offset:51200
	ds_read2st64_b32 v[230:231], v3 offset0:16 offset1:20
	ds_read_u16 v232, v20 offset:35328
	ds_read_u16 v233, v20 offset:51712
	ds_read_u16 v234, v20 offset:35840
	ds_read_u16 v235, v20 offset:52224
	ds_read2st64_b32 v[236:237], v3 offset0:24 offset1:28
	ds_read_u16 v238, v20 offset:36352
	ds_read_u16 v239, v20 offset:52736
	s_waitcnt lgkmcnt(15)
	v_mov_b32_e32 v4, v216
	v_lshlrev_b32_e32 v4, 16, v4
	v_add_f32_e32 v4, v7, v4
	v_mul_f32_e32 v4, 0xbfb8aa3b, v4
	v_exp_f32_e32 v4, v4
	s_waitcnt lgkmcnt(15)
	v_mov_b32_e32 v24, v217
	v_lshlrev_b32_e32 v24, 16, v24
	v_add_f32_e32 v24, v7, v24
	v_mul_f32_e32 v24, 0xbfb8aa3b, v24
	v_add_f32_e32 v4, 1.0, v4
	v_div_scale_f32 v5, s[2:3], v4, v4, 1.0
	v_rcp_f32_e32 v8, v5
	v_exp_f32_e32 v24, v24
	v_fma_f32 v9, -v5, v8, 1.0
	v_fmac_f32_e32 v8, v9, v8
	v_div_scale_f32 v9, vcc, 1.0, v4, 1.0
	v_mul_f32_e32 v13, v9, v8
	v_fma_f32 v17, -v5, v13, v9
	v_fmac_f32_e32 v13, v17, v8
	v_fma_f32 v5, -v5, v13, v9
	v_div_fmas_f32 v5, v5, v8, v13
	v_div_fixup_f32 v4, v5, v4, 1.0
	v_mul_f32_e32 v4, 0xc1000000, v4
	v_mul_f32_e32 v4, v19, v4
	v_add_f32_e32 v24, 1.0, v24
	s_waitcnt lgkmcnt(15)
	v_mov_b32_e32 v22, v218
	v_mov_b32_e32 v23, v219
	v_mov_b32_e32 v5, v220
	v_lshlrev_b32_e32 v5, 16, v5
	v_add_f32_e32 v5, v15, v5
	v_mul_f32_e32 v5, 0xbfb8aa3b, v5
	v_exp_f32_e32 v5, v5
	s_nop 0
	v_add_f32_e32 v5, 1.0, v5
	v_div_scale_f32 v8, s[2:3], v5, v5, 1.0
	v_rcp_f32_e32 v9, v8
	s_mov_b32 s2, 0xc8e0000
	v_fma_f32 v13, -v8, v9, 1.0
	v_fmac_f32_e32 v9, v13, v9
	v_div_scale_f32 v13, vcc, 1.0, v5, 1.0
	v_mul_f32_e32 v17, v13, v9
	v_fma_f32 v21, -v8, v17, v13
	v_fmac_f32_e32 v17, v21, v9
	v_fma_f32 v8, -v8, v17, v13
	v_div_fmas_f32 v8, v8, v9, v17
	v_div_fixup_f32 v5, v8, v5, 1.0
	v_mul_f32_e32 v8, 0x3fb8aa3b, v4
	v_add_f32_e32 v4, v4, v4
	v_fmamk_f32 v9, v4, 0x3ab60b61, v205
	v_exp_f32_e32 v8, v8
	v_fmaak_f32 v9, v4, v9, 0x3d2aaaab
	v_fmaak_f32 v9, v4, v9, 0x3e2aaaab
	v_fma_f32 v9, v4, v9, 0.5
	v_fma_f32 v9, v4, v9, 1.0
	v_mul_f32_e64 v9, v9, -v4
	v_cmp_lt_f32_e32 vcc, s95, v4
	v_fma_f32 v4, -v8, v8, 1.0
	v_mul_f32_e32 v5, v22, v5
	v_cndmask_b32_e32 v4, v4, v9, vcc
	v_sqrt_f32_e32 v4, v4
	v_mul_f32_e32 v22, v12, v8
	v_mul_f32_e32 v21, v5, v4
	v_fmac_f32_e32 v21, v16, v8
	v_lshl_add_u64 v[8:9], v[0:1], 0, s[42:43]
	v_add_co_u32_e32 v12, vcc, s2, v8
	s_mov_b32 s2, 0xc8e1000
	s_nop 0
	v_addc_co_u32_e32 v13, vcc, 0, v9, vcc
	v_add_co_u32_e32 v4, vcc, s2, v8
	s_mov_b32 s2, 0xd8e0000
	s_nop 0
	v_addc_co_u32_e32 v5, vcc, 0, v9, vcc
	v_add_co_u32_e32 v16, vcc, s2, v8
	s_mov_b32 s2, 0xd8e1000
	s_nop 0
	v_addc_co_u32_e32 v17, vcc, 0, v9, vcc
	v_add_co_u32_e32 v8, vcc, s2, v8
	v_div_scale_f32 v25, s[2:3], v24, v24, 1.0
	v_rcp_f32_e32 v26, v25
	v_addc_co_u32_e32 v9, vcc, 0, v9, vcc
	global_store_dword v[4:5], v21, off offset:-4096
	v_fma_f32 v27, -v25, v26, 1.0
	v_fmac_f32_e32 v26, v27, v26
	v_div_scale_f32 v27, vcc, 1.0, v24, 1.0
	v_mul_f32_e32 v28, v27, v26
	v_fma_f32 v29, -v25, v28, v27
	v_fmac_f32_e32 v28, v29, v26
	v_fma_f32 v25, -v25, v28, v27
	v_div_fmas_f32 v25, v25, v26, v28
	v_div_fixup_f32 v24, v25, v24, 1.0
	v_mul_f32_e32 v24, 0xc1000000, v24
	v_mul_f32_e32 v24, v19, v24
	global_store_dword v[8:9], v22, off offset:-4096
	s_add_u32 s42, s42, 0x2000
	s_waitcnt lgkmcnt(15)
	v_mov_b32_e32 v25, v221
	v_lshlrev_b32_e32 v25, 16, v25
	v_add_f32_e32 v25, v15, v25
	v_mul_f32_e32 v25, 0xbfb8aa3b, v25
	v_exp_f32_e32 v25, v25
	s_addc_u32 s43, s43, 0
	s_cmpk_eq_u32 s42, 0x8000
	v_add_f32_e32 v25, 1.0, v25
	v_div_scale_f32 v26, s[2:3], v25, v25, 1.0
	v_rcp_f32_e32 v27, v26
	s_nop 0
	v_fma_f32 v28, -v26, v27, 1.0
	v_fmac_f32_e32 v27, v28, v27
	v_div_scale_f32 v28, vcc, 1.0, v25, 1.0
	v_mul_f32_e32 v29, v28, v27
	v_fma_f32 v30, -v26, v29, v28
	v_fmac_f32_e32 v29, v30, v27
	v_fma_f32 v26, -v26, v29, v28
	v_div_fmas_f32 v26, v26, v27, v29
	v_div_fixup_f32 v25, v26, v25, 1.0
	v_mul_f32_e32 v26, 0x3fb8aa3b, v24
	v_add_f32_e32 v24, v24, v24
	v_fmamk_f32 v27, v24, 0x3ab60b61, v205
	v_exp_f32_e32 v26, v26
	v_fmaak_f32 v27, v24, v27, 0x3d2aaaab
	v_fmaak_f32 v27, v24, v27, 0x3e2aaaab
	v_fma_f32 v27, v24, v27, 0.5
	v_fma_f32 v27, v24, v27, 1.0
	v_mul_f32_e64 v27, v27, -v24
	v_cmp_lt_f32_e32 vcc, s95, v24
	v_fma_f32 v24, -v26, v26, 1.0
	v_mul_f32_e32 v23, v23, v25
	v_cndmask_b32_e32 v24, v24, v27, vcc
	v_sqrt_f32_e32 v24, v24
	s_nop 0
	v_mul_f32_e32 v24, v23, v24
	v_fmac_f32_e32 v24, v21, v26
	v_mul_f32_e32 v21, v22, v26
	global_store_dword v[12:13], v24, off offset:1024
	global_store_dword v[16:17], v21, off offset:1024
	s_waitcnt lgkmcnt(14)
	v_mov_b32_e32 v22, v222
	v_lshlrev_b32_e32 v22, 16, v22
	v_add_f32_e32 v22, v7, v22
	v_mul_f32_e32 v22, 0xbfb8aa3b, v22
	v_exp_f32_e32 v22, v22
	s_nop 0
	v_add_f32_e32 v22, 1.0, v22
	v_div_scale_f32 v23, s[2:3], v22, v22, 1.0
	v_rcp_f32_e32 v25, v23
	s_nop 0
	v_fma_f32 v26, -v23, v25, 1.0
	v_fmac_f32_e32 v25, v26, v25
	v_div_scale_f32 v26, vcc, 1.0, v22, 1.0
	v_mul_f32_e32 v27, v26, v25
	v_fma_f32 v28, -v23, v27, v26
	v_fmac_f32_e32 v27, v28, v25
	v_fma_f32 v23, -v23, v27, v26
	v_div_fmas_f32 v23, v23, v25, v27
	v_div_fixup_f32 v22, v23, v22, 1.0
	v_mul_f32_e32 v22, 0xc1000000, v22
	v_mul_f32_e32 v22, v19, v22
	s_waitcnt lgkmcnt(13)
	v_mov_b32_e32 v23, v223
	v_lshlrev_b32_e32 v23, 16, v23
	v_add_f32_e32 v23, v15, v23
	v_mul_f32_e32 v23, 0xbfb8aa3b, v23
	v_exp_f32_e32 v23, v23
	s_nop 0
	v_add_f32_e32 v23, 1.0, v23
	v_div_scale_f32 v25, s[2:3], v23, v23, 1.0
	v_rcp_f32_e32 v26, v25
	s_nop 0
	v_fma_f32 v27, -v25, v26, 1.0
	v_fmac_f32_e32 v26, v27, v26
	v_div_scale_f32 v27, vcc, 1.0, v23, 1.0
	v_mul_f32_e32 v28, v27, v26
	v_fma_f32 v29, -v25, v28, v27
	v_fmac_f32_e32 v28, v29, v26
	v_fma_f32 v25, -v25, v28, v27
	v_div_fmas_f32 v25, v25, v26, v28
	v_div_fixup_f32 v25, v25, v23, 1.0
	v_mul_f32_e32 v23, 0x3fb8aa3b, v22
	v_add_f32_e32 v22, v22, v22
	v_exp_f32_e32 v26, v23
	v_fmamk_f32 v23, v22, 0x3ab60b61, v205
	v_fmaak_f32 v23, v22, v23, 0x3d2aaaab
	v_fmaak_f32 v23, v22, v23, 0x3e2aaaab
	v_fma_f32 v23, v22, v23, 0.5
	v_fma_f32 v23, v22, v23, 1.0
	v_mul_f32_e64 v23, v23, -v22
	v_cmp_lt_f32_e32 vcc, s95, v22
	v_fma_f32 v22, -v26, v26, 1.0
	v_mul_f32_e32 v21, v21, v26
	v_cndmask_b32_e32 v22, v22, v23, vcc
	v_sqrt_f32_e32 v27, v22
	s_waitcnt lgkmcnt(12)
	v_mov_b32_e32 v22, v224
	v_mov_b32_e32 v23, v225
	v_mul_f32_e32 v22, v22, v25
	v_mul_f32_e32 v22, v22, v27
	v_fmac_f32_e32 v22, v24, v26
	global_store_dword v[12:13], v22, off offset:2048
	global_store_dword v[16:17], v21, off offset:2048
	s_waitcnt lgkmcnt(11)
	v_mov_b32_e32 v24, v226
	v_lshlrev_b32_e32 v24, 16, v24
	v_add_f32_e32 v24, v7, v24
	v_mul_f32_e32 v24, 0xbfb8aa3b, v24
	v_exp_f32_e32 v24, v24
	s_nop 0
	v_add_f32_e32 v24, 1.0, v24
	v_div_scale_f32 v25, s[2:3], v24, v24, 1.0
	v_rcp_f32_e32 v26, v25
	s_nop 0
	v_fma_f32 v27, -v25, v26, 1.0
	v_fmac_f32_e32 v26, v27, v26
	v_div_scale_f32 v27, vcc, 1.0, v24, 1.0
	v_mul_f32_e32 v28, v27, v26
	v_fma_f32 v29, -v25, v28, v27
	v_fmac_f32_e32 v28, v29, v26
	v_fma_f32 v25, -v25, v28, v27
	v_div_fmas_f32 v25, v25, v26, v28
	v_div_fixup_f32 v24, v25, v24, 1.0
	v_mul_f32_e32 v24, 0xc1000000, v24
	v_mul_f32_e32 v24, v19, v24
	s_waitcnt lgkmcnt(10)
	v_mov_b32_e32 v25, v227
	v_lshlrev_b32_e32 v25, 16, v25
	v_add_f32_e32 v25, v15, v25
	v_mul_f32_e32 v25, 0xbfb8aa3b, v25
	v_exp_f32_e32 v25, v25
	s_nop 0
	v_add_f32_e32 v25, 1.0, v25
	v_div_scale_f32 v26, s[2:3], v25, v25, 1.0
	v_rcp_f32_e32 v27, v26
	s_nop 0
	v_fma_f32 v28, -v26, v27, 1.0
	v_fmac_f32_e32 v27, v28, v27
	v_div_scale_f32 v28, vcc, 1.0, v25, 1.0
	v_mul_f32_e32 v29, v28, v27
	v_fma_f32 v30, -v26, v29, v28
	v_fmac_f32_e32 v29, v30, v27
	v_fma_f32 v26, -v26, v29, v28
	v_div_fmas_f32 v26, v26, v27, v29
	v_div_fixup_f32 v25, v26, v25, 1.0
	v_mul_f32_e32 v26, 0x3fb8aa3b, v24
	v_add_f32_e32 v24, v24, v24
	v_fmamk_f32 v27, v24, 0x3ab60b61, v205
	v_exp_f32_e32 v26, v26
	v_fmaak_f32 v27, v24, v27, 0x3d2aaaab
	v_fmaak_f32 v27, v24, v27, 0x3e2aaaab
	v_fma_f32 v27, v24, v27, 0.5
	v_fma_f32 v27, v24, v27, 1.0
	v_mul_f32_e64 v27, v27, -v24
	v_cmp_lt_f32_e32 vcc, s95, v24
	v_fma_f32 v24, -v26, v26, 1.0
	v_mul_f32_e32 v23, v23, v25
	v_cndmask_b32_e32 v24, v24, v27, vcc
	v_sqrt_f32_e32 v24, v24
	v_mul_f32_e32 v21, v21, v26
	v_mul_f32_e32 v23, v23, v24
	v_fmac_f32_e32 v23, v22, v26
	global_store_dword v[12:13], v23, off offset:3072
	global_store_dword v[16:17], v21, off offset:3072
	s_waitcnt lgkmcnt(9)
	v_mov_b32_e32 v12, v228
	v_lshlrev_b32_e32 v12, 16, v12
	v_add_f32_e32 v12, v7, v12
	v_mul_f32_e32 v12, 0xbfb8aa3b, v12
	v_exp_f32_e32 v12, v12
	s_nop 0
	v_add_f32_e32 v12, 1.0, v12
	v_div_scale_f32 v13, s[2:3], v12, v12, 1.0
	v_rcp_f32_e32 v16, v13
	s_nop 0
	v_fma_f32 v17, -v13, v16, 1.0
	v_fmac_f32_e32 v16, v17, v16
	v_div_scale_f32 v17, vcc, 1.0, v12, 1.0
	v_mul_f32_e32 v22, v17, v16
	v_fma_f32 v24, -v13, v22, v17
	v_fmac_f32_e32 v22, v24, v16
	v_fma_f32 v13, -v13, v22, v17
	v_div_fmas_f32 v13, v13, v16, v22
	v_div_fixup_f32 v12, v13, v12, 1.0
	v_mul_f32_e32 v12, 0xc1000000, v12
	v_mul_f32_e32 v12, v19, v12
	s_waitcnt lgkmcnt(8)
	v_mov_b32_e32 v13, v229
	v_lshlrev_b32_e32 v13, 16, v13
	v_add_f32_e32 v13, v15, v13
	v_mul_f32_e32 v13, 0xbfb8aa3b, v13
	v_exp_f32_e32 v13, v13
	s_nop 0
	v_add_f32_e32 v13, 1.0, v13
	v_div_scale_f32 v16, s[2:3], v13, v13, 1.0
	v_rcp_f32_e32 v17, v16
	s_nop 0
	v_fma_f32 v22, -v16, v17, 1.0
	v_fmac_f32_e32 v17, v22, v17
	v_div_scale_f32 v22, vcc, 1.0, v13, 1.0
	v_mul_f32_e32 v24, v22, v17
	v_fma_f32 v25, -v16, v24, v22
	v_fmac_f32_e32 v24, v25, v17
	v_fma_f32 v16, -v16, v24, v22
	v_div_fmas_f32 v16, v16, v17, v24
	v_div_fixup_f32 v16, v16, v13, 1.0
	v_mul_f32_e32 v13, 0x3fb8aa3b, v12
	v_add_f32_e32 v12, v12, v12
	v_exp_f32_e32 v17, v13
	v_fmamk_f32 v13, v12, 0x3ab60b61, v205
	v_fmaak_f32 v13, v12, v13, 0x3d2aaaab
	v_fmaak_f32 v13, v12, v13, 0x3e2aaaab
	v_fma_f32 v13, v12, v13, 0.5
	v_fma_f32 v13, v12, v13, 1.0
	v_mul_f32_e64 v13, v13, -v12
	v_cmp_lt_f32_e32 vcc, s95, v12
	v_fma_f32 v12, -v17, v17, 1.0
	s_nop 0
	v_cndmask_b32_e32 v12, v12, v13, vcc
	v_sqrt_f32_e32 v22, v12
	s_waitcnt lgkmcnt(7)
	v_mov_b32_e32 v12, v230
	v_mov_b32_e32 v13, v231
	v_mul_f32_e32 v12, v12, v16
	v_mul_f32_e32 v12, v12, v22
	v_fmac_f32_e32 v12, v23, v17
	v_mul_f32_e32 v16, v21, v17
	global_store_dword v[4:5], v12, off
	global_store_dword v[8:9], v16, off
	s_waitcnt lgkmcnt(6)
	v_mov_b32_e32 v17, v232
	v_lshlrev_b32_e32 v17, 16, v17
	v_add_f32_e32 v17, v7, v17
	v_mul_f32_e32 v17, 0xbfb8aa3b, v17
	v_exp_f32_e32 v17, v17
	s_nop 0
	v_add_f32_e32 v17, 1.0, v17
	v_div_scale_f32 v21, s[2:3], v17, v17, 1.0
	v_rcp_f32_e32 v22, v21
	s_nop 0
	v_fma_f32 v23, -v21, v22, 1.0
	v_fmac_f32_e32 v22, v23, v22
	v_div_scale_f32 v23, vcc, 1.0, v17, 1.0
	v_mul_f32_e32 v24, v23, v22
	v_fma_f32 v25, -v21, v24, v23
	v_fmac_f32_e32 v24, v25, v22
	v_fma_f32 v21, -v21, v24, v23
	v_div_fmas_f32 v21, v21, v22, v24
	v_div_fixup_f32 v17, v21, v17, 1.0
	v_mul_f32_e32 v17, 0xc1000000, v17
	v_mul_f32_e32 v17, v19, v17
	s_waitcnt lgkmcnt(5)
	v_mov_b32_e32 v21, v233
	v_lshlrev_b32_e32 v21, 16, v21
	v_add_f32_e32 v21, v15, v21
	v_mul_f32_e32 v21, 0xbfb8aa3b, v21
	v_exp_f32_e32 v21, v21
	s_nop 0
	v_add_f32_e32 v21, 1.0, v21
	v_div_scale_f32 v22, s[2:3], v21, v21, 1.0
	v_rcp_f32_e32 v23, v22
	s_nop 0
	v_fma_f32 v24, -v22, v23, 1.0
	v_fmac_f32_e32 v23, v24, v23
	v_div_scale_f32 v24, vcc, 1.0, v21, 1.0
	v_mul_f32_e32 v25, v24, v23
	v_fma_f32 v26, -v22, v25, v24
	v_fmac_f32_e32 v25, v26, v23
	v_fma_f32 v22, -v22, v25, v24
	v_div_fmas_f32 v22, v22, v23, v25
	v_div_fixup_f32 v21, v22, v21, 1.0
	v_mul_f32_e32 v22, 0x3fb8aa3b, v17
	v_add_f32_e32 v17, v17, v17
	v_fmamk_f32 v23, v17, 0x3ab60b61, v205
	v_exp_f32_e32 v22, v22
	v_fmaak_f32 v23, v17, v23, 0x3d2aaaab
	v_fmaak_f32 v23, v17, v23, 0x3e2aaaab
	v_fma_f32 v23, v17, v23, 0.5
	v_fma_f32 v23, v17, v23, 1.0
	v_mul_f32_e64 v23, v23, -v17
	v_cmp_lt_f32_e32 vcc, s95, v17
	v_fma_f32 v17, -v22, v22, 1.0
	v_mul_f32_e32 v13, v13, v21
	v_cndmask_b32_e32 v17, v17, v23, vcc
	v_sqrt_f32_e32 v17, v17
	v_mul_f32_e32 v16, v16, v22
	v_mul_f32_e32 v17, v13, v17
	v_fmac_f32_e32 v17, v12, v22
	global_store_dword v[4:5], v17, off offset:1024
	global_store_dword v[8:9], v16, off offset:1024
	s_waitcnt lgkmcnt(4)
	v_mov_b32_e32 v12, v234
	v_lshlrev_b32_e32 v12, 16, v12
	v_add_f32_e32 v12, v7, v12
	v_mul_f32_e32 v12, 0xbfb8aa3b, v12
	v_exp_f32_e32 v12, v12
	s_nop 0
	v_add_f32_e32 v12, 1.0, v12
	v_div_scale_f32 v13, s[2:3], v12, v12, 1.0
	v_rcp_f32_e32 v21, v13
	s_nop 0
	v_fma_f32 v22, -v13, v21, 1.0
	v_fmac_f32_e32 v21, v22, v21
	v_div_scale_f32 v22, vcc, 1.0, v12, 1.0
	v_mul_f32_e32 v23, v22, v21
	v_fma_f32 v24, -v13, v23, v22
	v_fmac_f32_e32 v23, v24, v21
	v_fma_f32 v13, -v13, v23, v22
	v_div_fmas_f32 v13, v13, v21, v23
	v_div_fixup_f32 v12, v13, v12, 1.0
	v_mul_f32_e32 v12, 0xc1000000, v12
	v_mul_f32_e32 v12, v19, v12
	s_waitcnt lgkmcnt(3)
	v_mov_b32_e32 v13, v235
	v_lshlrev_b32_e32 v13, 16, v13
	v_add_f32_e32 v13, v15, v13
	v_mul_f32_e32 v13, 0xbfb8aa3b, v13
	v_exp_f32_e32 v13, v13
	s_nop 0
	v_add_f32_e32 v13, 1.0, v13
	v_div_scale_f32 v21, s[2:3], v13, v13, 1.0
	v_rcp_f32_e32 v22, v21
	s_nop 0
	v_fma_f32 v23, -v21, v22, 1.0
	v_fmac_f32_e32 v22, v23, v22
	v_div_scale_f32 v23, vcc, 1.0, v13, 1.0
	v_mul_f32_e32 v24, v23, v22
	v_fma_f32 v25, -v21, v24, v23
	v_fmac_f32_e32 v24, v25, v22
	v_fma_f32 v21, -v21, v24, v23
	v_div_fmas_f32 v21, v21, v22, v24
	v_div_fixup_f32 v21, v21, v13, 1.0
	v_mul_f32_e32 v13, 0x3fb8aa3b, v12
	v_add_f32_e32 v12, v12, v12
	v_exp_f32_e32 v22, v13
	v_fmamk_f32 v13, v12, 0x3ab60b61, v205
	v_fmaak_f32 v13, v12, v13, 0x3d2aaaab
	v_fmaak_f32 v13, v12, v13, 0x3e2aaaab
	v_fma_f32 v13, v12, v13, 0.5
	v_fma_f32 v13, v12, v13, 1.0
	v_mul_f32_e64 v13, v13, -v12
	v_cmp_lt_f32_e32 vcc, s95, v12
	v_fma_f32 v12, -v22, v22, 1.0
	s_nop 0
	v_cndmask_b32_e32 v12, v12, v13, vcc
	v_sqrt_f32_e32 v23, v12
	v_add_u32_e32 v3, 0x2000, v3
	s_waitcnt lgkmcnt(2)
	v_mov_b32_e32 v12, v236
	v_mov_b32_e32 v13, v237
	v_mul_f32_e32 v12, v12, v21
	v_mul_f32_e32 v12, v12, v23
	v_fmac_f32_e32 v12, v17, v22
	v_mul_f32_e32 v17, v16, v22
	global_store_dword v[4:5], v12, off offset:2048
	global_store_dword v[8:9], v17, off offset:2048
	s_waitcnt lgkmcnt(1)
	v_mov_b32_e32 v16, v238
	v_lshlrev_b32_e32 v16, 16, v16
	v_add_f32_e32 v16, v7, v16
	v_mul_f32_e32 v16, 0xbfb8aa3b, v16
	v_exp_f32_e32 v16, v16
	s_nop 0
	v_add_f32_e32 v16, 1.0, v16
	v_div_scale_f32 v21, s[2:3], v16, v16, 1.0
	v_rcp_f32_e32 v22, v21
	s_nop 0
	v_fma_f32 v23, -v21, v22, 1.0
	v_fmac_f32_e32 v22, v23, v22
	v_div_scale_f32 v23, vcc, 1.0, v16, 1.0
	v_mul_f32_e32 v24, v23, v22
	v_fma_f32 v25, -v21, v24, v23
	v_fmac_f32_e32 v24, v25, v22
	v_fma_f32 v21, -v21, v24, v23
	v_div_fmas_f32 v21, v21, v22, v24
	v_div_fixup_f32 v16, v21, v16, 1.0
	v_mul_f32_e32 v16, 0xc1000000, v16
	v_mul_f32_e32 v16, v19, v16
	v_add_u32_e32 v20, 0x1000, v20
	s_waitcnt lgkmcnt(0)
	v_mov_b32_e32 v21, v239
	v_lshlrev_b32_e32 v21, 16, v21
	v_add_f32_e32 v21, v15, v21
	v_mul_f32_e32 v21, 0xbfb8aa3b, v21
	v_exp_f32_e32 v21, v21
	s_nop 0
	v_add_f32_e32 v21, 1.0, v21
	v_div_scale_f32 v22, s[2:3], v21, v21, 1.0
	v_rcp_f32_e32 v23, v22
	s_nop 0
	v_fma_f32 v24, -v22, v23, 1.0
	v_fmac_f32_e32 v23, v24, v23
	v_div_scale_f32 v24, vcc, 1.0, v21, 1.0
	v_mul_f32_e32 v25, v24, v23
	v_fma_f32 v26, -v22, v25, v24
	v_fmac_f32_e32 v25, v26, v23
	v_fma_f32 v22, -v22, v25, v24
	v_div_fmas_f32 v22, v22, v23, v25
	v_div_fixup_f32 v21, v22, v21, 1.0
	v_mul_f32_e32 v22, 0x3fb8aa3b, v16
	v_add_f32_e32 v16, v16, v16
	v_fmamk_f32 v23, v16, 0x3ab60b61, v205
	v_exp_f32_e32 v22, v22
	v_fmaak_f32 v23, v16, v23, 0x3d2aaaab
	v_fmaak_f32 v23, v16, v23, 0x3e2aaaab
	v_fma_f32 v23, v16, v23, 0.5
	v_fma_f32 v23, v16, v23, 1.0
	v_mul_f32_e64 v23, v23, -v16
	v_cmp_lt_f32_e32 vcc, s95, v16
	v_fma_f32 v16, -v22, v22, 1.0
	v_mul_f32_e32 v13, v13, v21
	v_cndmask_b32_e32 v16, v16, v23, vcc
	v_sqrt_f32_e32 v16, v16
	s_nop 0
	v_mul_f32_e32 v16, v13, v16
	v_fmac_f32_e32 v16, v12, v22
	v_mul_f32_e32 v12, v17, v22
	global_store_dword v[4:5], v16, off offset:3072
	global_store_dword v[8:9], v12, off offset:3072
	s_cbranch_scc0 .LBB0_326
	s_xor_b64 s[2:3], exec, -1
	s_branch .LBB0_313

.LBB0_432:
	v_mov_b32_e32 v90, v197
	s_nop 0
	v_and_b32_e32 v36, 15, v90
	v_bfe_u32 v91, v90, 4, 2
	v_mul_u32_u24_e32 v36, 0x90, v36
	v_lshl_add_u32 v98, v91, 4, v36
	v_add_u32_e32 v98, s99, v98
	ds_read_b128 v[36:39], v98
	ds_read_b128 v[86:89], v98 offset:64
	ds_read_b128 v[78:81], v98 offset:4608
	ds_read_b128 v[94:97], v98 offset:4672
	ds_read_b128 v[40:43], v98 offset:2304
	ds_read_b128 v[82:85], v98 offset:6912
	s_waitcnt lgkmcnt(5)
	v_mfma_f32_16x16x32_bf16 v[36:39], v[36:39], v[44:47], 0
	s_waitcnt lgkmcnt(3)
	v_mfma_f32_16x16x32_bf16 v[78:81], v[78:81], v[44:47], 0
	v_mfma_f32_16x16x32_bf16 v[86:89], v[86:89], v[48:51], v[36:39]
	s_nop 4
	ds_read_b128 v[36:39], v98 offset:2368
	s_waitcnt lgkmcnt(3)
	v_mfma_f32_16x16x32_bf16 v[78:81], v[94:97], v[48:51], v[78:81]
	ds_read_b128 v[94:97], v98 offset:6976
	s_waitcnt lgkmcnt(3)
	v_mfma_f32_16x16x32_bf16 v[40:43], v[40:43], v[44:47], 0
	s_waitcnt lgkmcnt(2)
	v_mfma_f32_16x16x32_bf16 v[82:85], v[82:85], v[44:47], 0
	s_waitcnt lgkmcnt(1)
	v_mfma_f32_16x16x32_bf16 v[38:41], v[36:39], v[48:51], v[40:43]
	v_max_f32_e32 v36, v88, v89
	s_waitcnt lgkmcnt(0)
	v_mfma_f32_16x16x32_bf16 v[82:85], v[94:97], v[48:51], v[82:85]
	v_bfe_u32 v186, v90, 2, 2
	v_lshlrev_b32_e32 v187, 3, v90
	v_lshl_or_b32 v186, v91, 2, v186
	v_and_b32_e32 v187, 24, v187
	v_mad_u32_u24 v186, v186, s0, v187
	v_add_u32_e32 v187, s101, v186
	v_add_u32_e32 v186, s100, v186
	ds_read_b64_tr_b16 v[154:155], v186 offset:9216
	ds_read_b64_tr_b16 v[156:157], v186 offset:11520
	ds_read_b64_tr_b16 v[158:159], v186 offset:9248
	ds_read_b64_tr_b16 v[160:161], v186 offset:11552
	ds_read_b64_tr_b16 v[162:163], v186 offset:9280
	ds_read_b64_tr_b16 v[164:165], v186 offset:11584
	ds_read_b64_tr_b16 v[166:167], v186 offset:9312
	ds_read_b64_tr_b16 v[168:169], v186 offset:11616
	ds_read_b64_tr_b16 v[170:171], v187 offset:13824
	ds_read_b64_tr_b16 v[172:173], v187 offset:16128
	ds_read_b64_tr_b16 v[174:175], v187 offset:13856
	ds_read_b64_tr_b16 v[176:177], v187 offset:16160
	ds_read_b64_tr_b16 v[178:179], v187 offset:13888
	ds_read_b64_tr_b16 v[180:181], v187 offset:16192
	ds_read_b64_tr_b16 v[182:183], v187 offset:13920
	ds_read_b64_tr_b16 v[184:185], v187 offset:16224
	v_max3_f32 v36, v86, v87, v36
	s_nop 1
	v_max_f32_e32 v37, v40, v41
	v_max3_f32 v37, v38, v39, v37
	v_max3_f32 v36, v36, s28, v37
	v_max_f32_e32 v37, v80, v81
	v_max_f32_e32 v43, v84, v84
	v_max_f32_e32 v42, v43, v85
	v_max3_f32 v37, v78, v79, v37
	v_max3_f32 v42, v82, v83, v42
	v_max3_f32 v36, v36, v37, v42
	v_mov_b32_e32 v37, v36
	s_nop 1
	v_permlane16_swap_b32_e32 v36, v37
	v_max_f32_e32 v36, v36, v37
	v_mov_b32_e32 v37, v36
	s_nop 1
	v_permlane32_swap_b32_e32 v36, v37
	v_max3_f32 v37, v17, v36, v37
	v_mul_f32_e32 v36, 0x3e38aa3b, v37
	v_cmp_ngt_f32_e32 vcc, s36, v37
	v_sub_f32_e32 v17, v17, v37
	v_mul_f32_e32 v17, 0x3e38aa3b, v17
	v_cndmask_b32_e32 v36, 0, v36, vcc
	v_fma_f32 v42, v86, s29, -v36
	v_exp_f32_e32 v86, v42
	v_fma_f32 v43, v87, s29, -v36
	v_exp_f32_e32 v87, v43
	v_fma_f32 v43, v88, s29, -v36
	v_exp_f32_e32 v88, v43
	v_fma_f32 v43, v89, s29, -v36
	v_exp_f32_e32 v89, v43
	v_fma_f32 v38, v38, s29, -v36
	v_add_f32_e32 v42, 0, v86
	v_exp_f32_e32 v94, v38
	v_fma_f32 v39, v39, s29, -v36
	v_add_f32_e32 v42, v87, v42
	v_exp_f32_e32 v39, v39
	v_fma_f32 v40, v40, s29, -v36
	v_add_f32_e32 v42, v88, v42
	v_exp_f32_e32 v95, v40
	v_fma_f32 v40, v41, s29, -v36
	v_add_f32_e32 v42, v89, v42
	v_exp_f32_e32 v96, v40
	v_fma_f32 v40, v78, s29, -v36
	v_add_f32_e32 v38, v94, v42
	v_exp_f32_e32 v97, v40
	v_fma_f32 v40, v79, s29, -v36
	v_add_f32_e32 v38, v39, v38
	v_exp_f32_e32 v98, v40
	v_fma_f32 v40, v80, s29, -v36
	v_add_f32_e32 v38, v95, v38
	v_exp_f32_e32 v99, v40
	v_fma_f32 v40, v81, s29, -v36
	v_add_f32_e32 v38, v96, v38
	v_exp_f32_e32 v100, v40
	v_fma_f32 v40, v82, s29, -v36
	v_add_f32_e32 v38, v97, v38
	v_exp_f32_e32 v101, v40
	v_fma_f32 v40, v83, s29, -v36
	v_add_f32_e32 v38, v98, v38
	v_exp_f32_e32 v102, v40
	v_fma_f32 v40, v84, s29, -v36
	v_add_f32_e32 v38, v99, v38
	v_exp_f32_e32 v103, v40
	v_fma_f32 v36, v85, s29, -v36
	v_add_f32_e32 v38, v100, v38
	v_exp_f32_e32 v104, v36
	v_add_f32_e32 v38, v101, v38
	v_exp_f32_e32 v36, v17
	v_add_f32_e32 v38, v102, v38
	v_add_f32_e32 v38, v103, v38
	v_add_f32_e32 v38, v104, v38
	v_fmac_f32_e32 v38, v16, v36
	v_pk_mul_f32 v[42:43], v[62:63], v[36:37] op_sel_hi:[1,0]
	v_pk_mul_f32 v[40:41], v[60:61], v[36:37] op_sel_hi:[1,0]
	v_pk_mul_f32 v[62:63], v[66:67], v[36:37] op_sel_hi:[1,0]
	v_pk_mul_f32 v[60:61], v[64:65], v[36:37] op_sel_hi:[1,0]
	v_pk_mul_f32 v[66:67], v[70:71], v[36:37] op_sel_hi:[1,0]
	v_pk_mul_f32 v[64:65], v[68:69], v[36:37] op_sel_hi:[1,0]
	v_pk_mul_f32 v[70:71], v[74:75], v[36:37] op_sel_hi:[1,0]
	v_pk_mul_f32 v[68:69], v[72:73], v[36:37] op_sel_hi:[1,0]
	v_cvt_pk_bf16_f32 v72, v86, v87
	v_cvt_pk_bf16_f32 v73, v88, v89
	v_cvt_pk_bf16_f32 v74, v94, v39
	v_cvt_pk_bf16_f32 v75, v95, v96
	v_cvt_pk_bf16_f32 v86, v97, v98
	v_cvt_pk_bf16_f32 v87, v99, v100
	v_cvt_pk_bf16_f32 v88, v101, v102
	v_cvt_pk_bf16_f32 v89, v103, v104
	v_cmp_ne_u32_e32 vcc, 3, v77
	s_waitcnt lgkmcnt(14)
	v_mfma_f32_16x16x32_bf16 v[40:43], v[154:157], v[72:75], v[40:43]
	s_waitcnt lgkmcnt(12)
	v_mfma_f32_16x16x32_bf16 v[78:81], v[158:161], v[72:75], v[60:63]
	s_and_b64 vcc, exec, vcc
	s_waitcnt lgkmcnt(10)
	v_mfma_f32_16x16x32_bf16 v[82:85], v[162:165], v[72:75], v[64:67]
	s_waitcnt lgkmcnt(8)
	v_mfma_f32_16x16x32_bf16 v[72:75], v[166:169], v[72:75], v[68:71]
	s_waitcnt lgkmcnt(6)
	v_mfma_f32_16x16x32_bf16 v[60:63], v[170:173], v[86:89], v[40:43]
	s_waitcnt lgkmcnt(4)
	v_mfma_f32_16x16x32_bf16 v[64:67], v[174:177], v[86:89], v[78:81]
	s_waitcnt lgkmcnt(2)
	v_mfma_f32_16x16x32_bf16 v[68:71], v[178:181], v[86:89], v[82:85]
	s_waitcnt lgkmcnt(0)
	v_mfma_f32_16x16x32_bf16 v[72:75], v[182:185], v[86:89], v[72:75]
	s_cbranch_vccnz .LBB0_421
	v_mov_b32_e32 v16, v38
	v_mov_b32_e32 v17, v38
	s_nop 1
	v_permlane16_swap_b32_e32 v16, v17
	v_add_f32_e32 v39, v16, v17
	v_mov_b32_e32 v40, v39
	s_nop 1
	v_permlane32_swap_b32_e32 v39, v40
	s_and_saveexec_b64 s[10:11], s[42:43]
	s_cbranch_execz .LBB0_420
	v_lshlrev_b32_e32 v41, 2, v1
	ds_read2st64_b32 v[16:17], v41 offset0:208 offset1:210
	s_movk_i32 s17, 0x110
	v_mad_u64_u32 v[82:83], s[20:21], v1, s17, v[4:5]
	s_nop 0
	ds_read_b128 v[78:81], v82 offset:18432
	ds_read_b128 v[232:235], v82 offset:18496
	ds_read_b128 v[236:239], v82 offset:18560
	ds_read_b128 v[240:243], v82 offset:18624
	s_waitcnt lgkmcnt(4)
	v_max_f32_e32 v36, v16, v16
	v_max_f32_e32 v42, v36, v37
	v_sub_f32_e32 v36, v37, v42
	v_sub_f32_e32 v16, v16, v42
	v_mul_f32_e32 v36, 0x3e38aa3b, v36
	v_mul_f32_e32 v16, 0x3e38aa3b, v16
	v_exp_f32_e32 v36, v36
	v_exp_f32_e32 v16, v16
	v_pk_mul_f32 v[84:85], v[62:63], v[36:37] op_sel_hi:[1,0]
	v_pk_mul_f32 v[86:87], v[60:61], v[36:37] op_sel_hi:[1,0]
	s_waitcnt lgkmcnt(3)
	v_pk_fma_f32 v[80:81], v[80:81], v[16:17], v[84:85] op_sel_hi:[1,0,1]
	v_pk_fma_f32 v[78:79], v[78:79], v[16:17], v[86:87] op_sel_hi:[1,0,1]
	ds_write_b128 v82, v[78:81] offset:18432
	v_pk_mul_f32 v[84:85], v[66:67], v[36:37] op_sel_hi:[1,0]
	v_pk_mul_f32 v[86:87], v[64:65], v[36:37] op_sel_hi:[1,0]
	s_waitcnt lgkmcnt(3)
	v_pk_fma_f32 v[234:235], v[234:235], v[16:17], v[84:85] op_sel_hi:[1,0,1]
	v_pk_fma_f32 v[232:233], v[232:233], v[16:17], v[86:87] op_sel_hi:[1,0,1]
	ds_write_b128 v82, v[232:235] offset:18496
	v_pk_mul_f32 v[84:85], v[70:71], v[36:37] op_sel_hi:[1,0]
	v_pk_mul_f32 v[86:87], v[68:69], v[36:37] op_sel_hi:[1,0]
	s_waitcnt lgkmcnt(3)
	v_pk_fma_f32 v[238:239], v[16:17], v[238:239], v[84:85] op_sel_hi:[0,1,1]
	v_pk_fma_f32 v[236:237], v[16:17], v[236:237], v[86:87] op_sel_hi:[0,1,1]
	ds_write_b128 v82, v[236:239] offset:18560
	s_waitcnt lgkmcnt(3)
	v_pk_mul_f32 v[242:243], v[16:17], v[242:243] op_sel_hi:[0,1]
	v_pk_mul_f32 v[240:241], v[16:17], v[240:241] op_sel_hi:[0,1]
	v_pk_fma_f32 v[242:243], v[74:75], v[36:37], v[242:243] op_sel_hi:[1,0,1]
	v_pk_fma_f32 v[240:241], v[72:73], v[36:37], v[240:241] op_sel_hi:[1,0,1]
	ds_write_b128 v82, v[240:243] offset:18624
	s_and_b64 exec, exec, s[38:39]
	s_cbranch_execz .LBB0_420
	v_add_f32_e32 v39, v39, v40
	v_mul_f32_e32 v36, v39, v36
	v_fmac_f32_e32 v36, v17, v16
	ds_write2st64_b32 v41, v42, v36 offset0:208 offset1:210
	s_branch .LBB0_420
